# v20 + adaLN GEMV main loop rewritten by hand: 16 weight rows (2 batches of 8 loads) in flight per thread instead of 8
# speedup vs baseline: 1.0058x; 1.0030x over previous
; #define LAS __attribute__((address_space(3)))
; __global__ void __launch_bounds__(NWAVES * 64, 2) fwd_kernel(Args args) {
;     ...
;             for (int g = vcu; g < NMOD / 96; g += G) {
;                 if (kg < 21) {
;                     f32x4 a0 = {0.f, 0.f, 0.f, 0.f}, a1 = {0.f, 0.f, 0.f, 0.f};
;                     const float* wp = w_ada + (size_t)g * 96 + cg * 4;
; #pragma unroll 8
;                     for (int k = kg; k < D; k += 21) { const f32x4 w = *(const f32x4*)(wp + (size_t)k * NMOD); const float c0 = cact[k], c1 = cact[D + k]; a0 += w * c0; a1 += w * c1; }
;                     LAS float* rp = red + (kg * 24 + cg) * 8;
;                     rp[0] = a0.x; rp[1] = a0.y; rp[2] = a0.z; rp[3] = a0.w; rp[4] = a1.x; rp[5] = a1.y; rp[6] = a1.z; rp[7] = a1.w;
;                 }
.LBB0_25:
	v_lshl_add_u64 v[92:93], v[18:19], 0, v[16:17]
	s_mov_b64 s[0:1], 0x1f8000
	v_lshl_add_u64 v[94:95], v[92:93], 0, s[0:1]
	v_lshl_add_u64 v[96:97], v[94:95], 0, s[0:1]
	v_lshl_add_u64 v[98:99], v[96:97], 0, s[0:1]
	v_lshl_add_u64 v[100:101], v[98:99], 0, s[0:1]
	v_lshl_add_u64 v[102:103], v[100:101], 0, s[0:1]
	v_lshl_add_u64 v[104:105], v[102:103], 0, s[0:1]
	v_lshl_add_u64 v[106:107], v[104:105], 0, s[0:1]
	v_lshl_add_u64 v[108:109], v[106:107], 0, s[0:1]
	v_lshl_add_u64 v[110:111], v[108:109], 0, s[0:1]
	v_lshl_add_u64 v[112:113], v[110:111], 0, s[0:1]
	v_lshl_add_u64 v[114:115], v[112:113], 0, s[0:1]
	v_lshl_add_u64 v[116:117], v[114:115], 0, s[0:1]
	v_lshl_add_u64 v[118:119], v[116:117], 0, s[0:1]
	v_lshl_add_u64 v[120:121], v[118:119], 0, s[0:1]
	v_lshl_add_u64 v[122:123], v[120:121], 0, s[0:1]
	global_load_dwordx4 v[28:31], v[92:93], off
	global_load_dwordx4 v[32:35], v[94:95], off
	global_load_dwordx4 v[36:39], v[96:97], off
	global_load_dwordx4 v[40:43], v[98:99], off
	global_load_dwordx4 v[44:47], v[100:101], off
	global_load_dwordx4 v[48:51], v[102:103], off
	global_load_dwordx4 v[52:55], v[104:105], off
	global_load_dwordx4 v[56:59], v[106:107], off
	global_load_dwordx4 v[124:127], v[108:109], off
	global_load_dwordx4 v[128:131], v[110:111], off
	global_load_dwordx4 v[132:135], v[112:113], off
	global_load_dwordx4 v[136:139], v[114:115], off
	global_load_dwordx4 v[140:143], v[116:117], off
	global_load_dwordx4 v[144:147], v[118:119], off
	global_load_dwordx4 v[148:151], v[120:121], off
	global_load_dwordx4 v[152:155], v[122:123], off
	v_add_u32_e32 v199, 0x4000, v27
	ds_read2_b32 v[60:61], v27 offset1:21
	ds_read2_b32 v[62:63], v27 offset0:42 offset1:63
	ds_read2_b32 v[64:65], v27 offset0:84 offset1:105
	ds_read2_b32 v[66:67], v27 offset0:126 offset1:147
	ds_read2_b32 v[68:69], v199 offset1:21
	ds_read2_b32 v[70:71], v199 offset0:42 offset1:63
	ds_read2_b32 v[72:73], v199 offset0:84 offset1:105
	ds_read2_b32 v[74:75], v199 offset0:126 offset1:147
	s_waitcnt lgkmcnt(0)
	v_mov_b32_e32 v76, v61
	v_mov_b32_e32 v84, v69
	v_mov_b32_e32 v78, v63
	v_mov_b32_e32 v86, v71
	v_mov_b32_e32 v80, v65
	v_mov_b32_e32 v88, v73
	v_mov_b32_e32 v82, v67
	v_mov_b32_e32 v90, v75
	s_waitcnt vmcnt(15)
	v_pk_fma_f32 v[6:7], v[30:31], v[60:61], v[6:7] op_sel_hi:[1,0,1]
	v_pk_fma_f32 v[4:5], v[28:29], v[60:61], v[4:5] op_sel_hi:[1,0,1]
	v_pk_fma_f32 v[10:11], v[30:31], v[68:69], v[10:11] op_sel_hi:[1,0,1]
	v_pk_fma_f32 v[8:9], v[28:29], v[68:69], v[8:9] op_sel_hi:[1,0,1]
	s_waitcnt vmcnt(14)
	v_pk_fma_f32 v[6:7], v[34:35], v[76:77], v[6:7] op_sel_hi:[1,0,1]
	v_pk_fma_f32 v[4:5], v[32:33], v[76:77], v[4:5] op_sel_hi:[1,0,1]
	v_pk_fma_f32 v[10:11], v[34:35], v[84:85], v[10:11] op_sel_hi:[1,0,1]
	v_pk_fma_f32 v[8:9], v[32:33], v[84:85], v[8:9] op_sel_hi:[1,0,1]
	s_waitcnt vmcnt(13)
	v_pk_fma_f32 v[6:7], v[38:39], v[62:63], v[6:7] op_sel_hi:[1,0,1]
	v_pk_fma_f32 v[4:5], v[36:37], v[62:63], v[4:5] op_sel_hi:[1,0,1]
	v_pk_fma_f32 v[10:11], v[38:39], v[70:71], v[10:11] op_sel_hi:[1,0,1]
	v_pk_fma_f32 v[8:9], v[36:37], v[70:71], v[8:9] op_sel_hi:[1,0,1]
	s_waitcnt vmcnt(12)
	v_pk_fma_f32 v[6:7], v[42:43], v[78:79], v[6:7] op_sel_hi:[1,0,1]
	v_pk_fma_f32 v[4:5], v[40:41], v[78:79], v[4:5] op_sel_hi:[1,0,1]
	v_pk_fma_f32 v[10:11], v[42:43], v[86:87], v[10:11] op_sel_hi:[1,0,1]
	v_pk_fma_f32 v[8:9], v[40:41], v[86:87], v[8:9] op_sel_hi:[1,0,1]
	s_waitcnt vmcnt(11)
	v_pk_fma_f32 v[6:7], v[46:47], v[64:65], v[6:7] op_sel_hi:[1,0,1]
	v_pk_fma_f32 v[4:5], v[44:45], v[64:65], v[4:5] op_sel_hi:[1,0,1]
	v_pk_fma_f32 v[10:11], v[46:47], v[72:73], v[10:11] op_sel_hi:[1,0,1]
	v_pk_fma_f32 v[8:9], v[44:45], v[72:73], v[8:9] op_sel_hi:[1,0,1]
	s_waitcnt vmcnt(10)
	v_pk_fma_f32 v[6:7], v[50:51], v[80:81], v[6:7] op_sel_hi:[1,0,1]
	v_pk_fma_f32 v[4:5], v[48:49], v[80:81], v[4:5] op_sel_hi:[1,0,1]
	v_pk_fma_f32 v[10:11], v[50:51], v[88:89], v[10:11] op_sel_hi:[1,0,1]
	v_pk_fma_f32 v[8:9], v[48:49], v[88:89], v[8:9] op_sel_hi:[1,0,1]
	s_waitcnt vmcnt(9)
; #define LAS __attribute__((address_space(3)))
; __global__ void __launch_bounds__(NWAVES * 64, 2) fwd_kernel(Args args) {
;     ...
;             for (int g = vcu; g < NMOD / 96; g += G) {
;                 if (kg < 21) {
;                     f32x4 a0 = {0.f, 0.f, 0.f, 0.f}, a1 = {0.f, 0.f, 0.f, 0.f};
;                     const float* wp = w_ada + (size_t)g * 96 + cg * 4;
; #pragma unroll 8
;                     for (int k = kg; k < D; k += 21) { const f32x4 w = *(const f32x4*)(wp + (size_t)k * NMOD); const float c0 = cact[k], c1 = cact[D + k]; a0 += w * c0; a1 += w * c1; }
;                     LAS float* rp = red + (kg * 24 + cg) * 8;
;                     rp[0] = a0.x; rp[1] = a0.y; rp[2] = a0.z; rp[3] = a0.w; rp[4] = a1.x; rp[5] = a1.y; rp[6] = a1.z; rp[7] = a1.w;
;                 }
	v_pk_fma_f32 v[6:7], v[54:55], v[66:67], v[6:7] op_sel_hi:[1,0,1]
	v_pk_fma_f32 v[4:5], v[52:53], v[66:67], v[4:5] op_sel_hi:[1,0,1]
	v_pk_fma_f32 v[10:11], v[54:55], v[74:75], v[10:11] op_sel_hi:[1,0,1]
	v_pk_fma_f32 v[8:9], v[52:53], v[74:75], v[8:9] op_sel_hi:[1,0,1]
	s_waitcnt vmcnt(8)
	v_pk_fma_f32 v[6:7], v[58:59], v[82:83], v[6:7] op_sel_hi:[1,0,1]
	v_pk_fma_f32 v[4:5], v[56:57], v[82:83], v[4:5] op_sel_hi:[1,0,1]
	v_pk_fma_f32 v[10:11], v[58:59], v[90:91], v[10:11] op_sel_hi:[1,0,1]
	v_pk_fma_f32 v[8:9], v[56:57], v[90:91], v[8:9] op_sel_hi:[1,0,1]
	v_add_u32_e32 v198, 0x2a0, v27
	v_add_u32_e32 v199, 0x42a0, v27
	ds_read2_b32 v[156:157], v198 offset1:21
	ds_read2_b32 v[158:159], v198 offset0:42 offset1:63
	ds_read2_b32 v[160:161], v198 offset0:84 offset1:105
	ds_read2_b32 v[162:163], v198 offset0:126 offset1:147
	ds_read2_b32 v[164:165], v199 offset1:21
	ds_read2_b32 v[166:167], v199 offset0:42 offset1:63
	ds_read2_b32 v[168:169], v199 offset0:84 offset1:105
	ds_read2_b32 v[170:171], v199 offset0:126 offset1:147
	s_waitcnt lgkmcnt(0)
	v_mov_b32_e32 v182, v157
	v_mov_b32_e32 v190, v165
	v_mov_b32_e32 v184, v159
	v_mov_b32_e32 v192, v167
	v_mov_b32_e32 v186, v161
	v_mov_b32_e32 v194, v169
	v_mov_b32_e32 v188, v163
	v_mov_b32_e32 v196, v171
	s_waitcnt vmcnt(7)
	v_pk_fma_f32 v[6:7], v[126:127], v[156:157], v[6:7] op_sel_hi:[1,0,1]
	v_pk_fma_f32 v[4:5], v[124:125], v[156:157], v[4:5] op_sel_hi:[1,0,1]
	v_pk_fma_f32 v[10:11], v[126:127], v[164:165], v[10:11] op_sel_hi:[1,0,1]
	v_pk_fma_f32 v[8:9], v[124:125], v[164:165], v[8:9] op_sel_hi:[1,0,1]
	s_waitcnt vmcnt(6)
	v_pk_fma_f32 v[6:7], v[130:131], v[182:183], v[6:7] op_sel_hi:[1,0,1]
	v_pk_fma_f32 v[4:5], v[128:129], v[182:183], v[4:5] op_sel_hi:[1,0,1]
	v_pk_fma_f32 v[10:11], v[130:131], v[190:191], v[10:11] op_sel_hi:[1,0,1]
	v_pk_fma_f32 v[8:9], v[128:129], v[190:191], v[8:9] op_sel_hi:[1,0,1]
	s_waitcnt vmcnt(5)
	v_pk_fma_f32 v[6:7], v[134:135], v[158:159], v[6:7] op_sel_hi:[1,0,1]
	v_pk_fma_f32 v[4:5], v[132:133], v[158:159], v[4:5] op_sel_hi:[1,0,1]
	v_pk_fma_f32 v[10:11], v[134:135], v[166:167], v[10:11] op_sel_hi:[1,0,1]
	v_pk_fma_f32 v[8:9], v[132:133], v[166:167], v[8:9] op_sel_hi:[1,0,1]
	s_waitcnt vmcnt(4)
	v_pk_fma_f32 v[6:7], v[138:139], v[184:185], v[6:7] op_sel_hi:[1,0,1]
	v_pk_fma_f32 v[4:5], v[136:137], v[184:185], v[4:5] op_sel_hi:[1,0,1]
	v_pk_fma_f32 v[10:11], v[138:139], v[192:193], v[10:11] op_sel_hi:[1,0,1]
	v_pk_fma_f32 v[8:9], v[136:137], v[192:193], v[8:9] op_sel_hi:[1,0,1]
	s_waitcnt vmcnt(3)
	v_pk_fma_f32 v[6:7], v[142:143], v[160:161], v[6:7] op_sel_hi:[1,0,1]
	v_pk_fma_f32 v[4:5], v[140:141], v[160:161], v[4:5] op_sel_hi:[1,0,1]
	v_pk_fma_f32 v[10:11], v[142:143], v[168:169], v[10:11] op_sel_hi:[1,0,1]
	v_pk_fma_f32 v[8:9], v[140:141], v[168:169], v[8:9] op_sel_hi:[1,0,1]
	s_waitcnt vmcnt(2)
	v_pk_fma_f32 v[6:7], v[146:147], v[186:187], v[6:7] op_sel_hi:[1,0,1]
	v_pk_fma_f32 v[4:5], v[144:145], v[186:187], v[4:5] op_sel_hi:[1,0,1]
	v_pk_fma_f32 v[10:11], v[146:147], v[194:195], v[10:11] op_sel_hi:[1,0,1]
	v_pk_fma_f32 v[8:9], v[144:145], v[194:195], v[8:9] op_sel_hi:[1,0,1]
	s_waitcnt vmcnt(1)
	v_pk_fma_f32 v[6:7], v[150:151], v[162:163], v[6:7] op_sel_hi:[1,0,1]
	v_pk_fma_f32 v[4:5], v[148:149], v[162:163], v[4:5] op_sel_hi:[1,0,1]
	v_pk_fma_f32 v[10:11], v[150:151], v[170:171], v[10:11] op_sel_hi:[1,0,1]
	v_pk_fma_f32 v[8:9], v[148:149], v[170:171], v[8:9] op_sel_hi:[1,0,1]
	s_waitcnt vmcnt(0)
	v_pk_fma_f32 v[6:7], v[154:155], v[188:189], v[6:7] op_sel_hi:[1,0,1]
	v_pk_fma_f32 v[4:5], v[152:153], v[188:189], v[4:5] op_sel_hi:[1,0,1]
	v_pk_fma_f32 v[10:11], v[154:155], v[196:197], v[10:11] op_sel_hi:[1,0,1]
	v_pk_fma_f32 v[8:9], v[152:153], v[196:197], v[8:9] op_sel_hi:[1,0,1]
	v_add_u32_e32 v3, 0x150, v3
	v_cmp_lt_u32_e64 s[0:1], s8, v3
	v_lshl_add_u64 v[18:19], v[18:19], 0, s[40:41]
	v_lshl_add_u64 v[18:19], v[18:19], 0, s[40:41]
	v_add_u32_e32 v27, 0x540, v27
	s_or_b64 s[94:95], s[0:1], s[94:95]
	s_andn2_b64 exec, exec, s[94:95]
	s_cbranch_execnz .LBB0_25
	s_or_b64 exec, exec, s[94:95]
	ds_write_b128 v25, v[4:7] offset:32768
	ds_write_b128 v25, v[8:11] offset:32784
